# weight conversion split variant: jobs 8..14 (W_down, W_ple gate/proj, small) converted at start of phase 1 by workgroups 64..255; phase 0 keeps jobs 0..7
# speedup vs baseline: 1.0059x; 1.0059x over previous
.LBB0_560:
	s_andn2_b64 vcc, exec, s[12:13]
	s_cbranch_vccnz .LBB0_677
	s_movk_i32 s99, 8
	s_mov_b32 s38, 0
	s_mov_b32 s4, s54
	s_cmp_lg_u32 s53, 0
	s_cbranch_scc0 .Lcv_go
	s_cmp_lt_u32 s73, 64
	s_cbranch_scc1 .LBB0_677
	s_movk_i32 s99, 15
	s_mov_b32 s38, 8
	s_sub_i32 s4, s54, 64
	s_sub_i32 s73, s73, 64
